# P1 rmsnorm row loop: g loads hoisted, next row prefetched while the current one is reduced (unrolled by two)
# speedup vs baseline: 1.0079x; 1.0006x over previous
.LBB0_33:
	s_or_b64 exec, exec, s[16:17]
	s_cmp_eq_u32 s0, 0
	s_cselect_b64 s[14:15], -1, 0
	s_cmpk_lt_i32 s6, 0x4000
	s_cselect_b64 s[2:3], -1, 0
	s_and_b64 s[2:3], s[14:15], s[2:3]
	s_andn2_b64 vcc, exec, s[2:3]
	s_cbranch_vccnz .LBB0_36
	v_and_b32_e32 v2, 64, v227
	v_add_u32_e32 v2, 64, v2
	v_xor_b32_e32 v3, 1, v227
	v_cmp_lt_i32_e32 vcc, v3, v2
	v_readlane_b32 s16, v254, 0
	v_readlane_b32 s36, v254, 10
	v_cndmask_b32_e32 v3, v227, v3, vcc
	v_lshlrev_b32_e32 v6, 2, v3
	v_xor_b32_e32 v3, 2, v227
	v_cmp_lt_i32_e32 vcc, v3, v2
	s_and_b64 s[2:3], s[14:15], exec
	v_readlane_b32 s22, v254, 6
	v_cndmask_b32_e32 v3, v227, v3, vcc
	v_lshlrev_b32_e32 v7, 2, v3
	v_xor_b32_e32 v3, 4, v227
	v_cmp_lt_i32_e32 vcc, v3, v2
	v_readlane_b32 s23, v254, 7
	v_readlane_b32 s37, v254, 11
	v_cndmask_b32_e32 v3, v227, v3, vcc
	v_lshlrev_b32_e32 v8, 2, v3
	v_xor_b32_e32 v3, 8, v227
	v_cmp_lt_i32_e32 vcc, v3, v2
	s_cselect_b32 s2, s37, s23
	s_cselect_b32 s3, s36, s22
	v_cndmask_b32_e32 v3, v227, v3, vcc
	v_lshlrev_b32_e32 v9, 2, v3
	v_xor_b32_e32 v3, 16, v227
	s_lshl_b32 s0, s0, 10
	v_cmp_lt_i32_e32 vcc, v3, v2
	s_ashr_i32 s1, s0, 31
	v_readlane_b32 s40, v254, 14
	v_cndmask_b32_e32 v3, v227, v3, vcc
	s_lshl_b64 s[0:1], s[0:1], 2
	v_lshlrev_b32_e32 v10, 2, v3
	v_xor_b32_e32 v3, 32, v227
	v_readlane_b32 s41, v254, 15
	s_add_u32 s0, s40, s0
	v_cmp_lt_i32_e32 vcc, v3, v2
	s_addc_u32 s1, s41, s1
	v_lshlrev_b32_e32 v196, 4, v1
	v_cndmask_b32_e32 v2, v227, v3, vcc
	s_ashr_i32 s7, s6, 31
	v_lshlrev_b32_e32 v11, 2, v2
	v_lshl_add_u64 v[2:3], s[0:1], 0, v[196:197]
	s_lshl_b64 s[0:1], s[6:7], 11
	s_add_u32 s0, s12, s0
	v_mov_b32_e32 v1, v197
	s_addc_u32 s1, s13, s1
	v_lshl_add_u64 v[0:1], s[0:1], 0, v[0:1]
	s_mov_b64 s[0:1], 0xae00600
	s_ashr_i32 s9, s8, 31
	v_lshl_add_u64 v[0:1], v[0:1], 0, s[0:1]
	s_lshl_b64 s[12:13], s[8:9], 11
	s_lshl_b64 s[0:1], s[6:7], 12
	s_add_u32 s0, s3, s0
	s_addc_u32 s1, s2, s1
	v_lshl_add_u64 v[4:5], s[0:1], 0, v[196:197]
	v_lshl_add_u64 v[4:5], v[4:5], 0, s[34:35]
	s_lshl_b64 s[14:15], s[8:9], 12
	v_readlane_b32 s17, v254, 1
	v_readlane_b32 s18, v254, 2
	v_readlane_b32 s19, v254, 3
	v_readlane_b32 s20, v254, 4
	v_readlane_b32 s21, v254, 5
	v_readlane_b32 s38, v254, 12
	v_readlane_b32 s39, v254, 13
	v_readlane_b32 s42, v254, 16
	v_readlane_b32 s43, v254, 17
	v_readlane_b32 s44, v254, 18
	v_readlane_b32 s45, v254, 19
	v_readlane_b32 s46, v254, 20
	v_readlane_b32 s47, v254, 21
	v_readlane_b32 s48, v254, 22
	v_readlane_b32 s49, v254, 23
	v_readlane_b32 s50, v254, 24
	v_readlane_b32 s51, v254, 25
	global_load_dwordx4 v[56:59], v[2:3], off
	global_load_dwordx4 v[60:63], v[2:3], off offset:1024
	global_load_dwordx4 v[64:67], v[2:3], off offset:2048
	global_load_dwordx4 v[68:71], v[2:3], off offset:3072
	global_load_dwordx4 v[12:15], v[4:5], off offset:-2048
	global_load_dwordx4 v[16:19], v[4:5], off offset:-1024
	global_load_dwordx4 v[20:23], v[4:5], off
	global_load_dwordx4 v[24:27], v[4:5], off offset:1024
	v_lshl_add_u64 v[4:5], v[4:5], 0, s[14:15]
.LBB0_35:
	s_add_i32 s6, s6, s8
	s_cmpk_lt_i32 s6, 0x4000
	s_cbranch_scc0 .Lp1_np_a
	global_load_dwordx4 v[72:75], v[4:5], off offset:-2048
	global_load_dwordx4 v[76:79], v[4:5], off offset:-1024
	global_load_dwordx4 v[80:83], v[4:5], off
	global_load_dwordx4 v[84:87], v[4:5], off offset:1024
	v_lshl_add_u64 v[4:5], v[4:5], 0, s[14:15]
	s_waitcnt vmcnt(4)
	s_branch .Lp1_go_a

.Lp1_go_a:
	v_pk_mul_f32 v[32:33], v[14:15], v[14:15]
	v_pk_mul_f32 v[34:35], v[12:13], v[12:13]
	v_pk_mul_f32 v[36:37], v[18:19], v[18:19]
	v_pk_mul_f32 v[38:39], v[16:17], v[16:17]
	v_pk_mov_b32 v[44:45], v[34:35], v[32:33] op_sel:[1,0]
	v_mov_b32_e32 v35, v33
	v_pk_mov_b32 v[32:33], v[38:39], v[36:37] op_sel:[1,0]
	v_mov_b32_e32 v39, v37
	v_mul_f32_e32 v43, v24, v24
	v_mul_f32_e32 v40, v21, v21
	v_mul_f32_e32 v42, v23, v23
	v_pk_add_f32 v[34:35], v[44:45], v[34:35]
	v_pk_add_f32 v[32:33], v[32:33], v[38:39]
	v_mul_f32_e32 v46, v25, v25
	v_mul_f32_e32 v47, v26, v26
	v_mul_f32_e32 v48, v27, v27
	v_pk_fma_f32 v[36:37], v[20:21], v[20:21], v[40:41] op_sel_hi:[1,1,0]
	v_pk_fma_f32 v[40:41], v[22:23], v[22:23], v[42:43] op_sel_hi:[1,1,0]
	v_pk_add_f32 v[34:35], v[34:35], v[34:35] op_sel:[0,1] op_sel_hi:[1,0]
	v_pk_add_f32 v[32:33], v[32:33], v[32:33] op_sel:[0,1] op_sel_hi:[1,0]
	v_mov_b32_e32 v37, v47
	v_mov_b32_e32 v41, v48
	v_mov_b32_e32 v35, v43
	v_mov_b32_e32 v33, v46
	v_pk_add_f32 v[36:37], v[36:37], v[40:41]
	v_pk_add_f32 v[32:33], v[34:35], v[32:33]
	s_nop 0
	v_pk_add_f32 v[32:33], v[32:33], v[36:37]
	s_nop 0
	v_add_f32_e32 v32, v32, v33
	ds_bpermute_b32 v33, v6, v32
	s_waitcnt lgkmcnt(0)
	v_add_f32_e32 v32, v32, v33
	ds_bpermute_b32 v33, v7, v32
	s_waitcnt lgkmcnt(0)
	v_add_f32_e32 v32, v32, v33
	ds_bpermute_b32 v33, v8, v32
	s_waitcnt lgkmcnt(0)
	v_add_f32_e32 v32, v32, v33
	ds_bpermute_b32 v33, v9, v32
	s_waitcnt lgkmcnt(0)
	v_add_f32_e32 v32, v32, v33
	ds_bpermute_b32 v33, v10, v32
	s_waitcnt lgkmcnt(0)
	v_add_f32_e32 v32, v32, v33
	ds_bpermute_b32 v33, v11, v32
	s_waitcnt lgkmcnt(0)
	v_add_f32_e32 v32, v32, v33
	v_fmamk_f32 v32, v32, 0x3a800000, v224
	v_mul_f32_e32 v33, 0x4b800000, v32
	v_cmp_gt_f32_e32 vcc, s85, v32
	s_nop 1
	v_cndmask_b32_e32 v32, v32, v33, vcc
	v_rsq_f32_e32 v32, v32
	s_nop 0
	v_mul_f32_e32 v33, 0x45800000, v32
	v_cndmask_b32_e32 v32, v32, v33, vcc
	v_mul_f32_e32 v12, v32, v12
	v_mul_f32_e32 v13, v32, v13
	v_mul_f32_e32 v14, v32, v14
	v_mul_f32_e32 v15, v32, v15
	v_mul_f32_e32 v12, v56, v12
	v_mul_f32_e32 v13, v57, v13
	v_mul_f32_e32 v14, v58, v14
	v_mul_f32_e32 v15, v59, v15
	v_cvt_pk_bf16_f32 v12, v12, v13
	v_cvt_pk_bf16_f32 v13, v14, v15
	global_store_dwordx2 v[0:1], v[12:13], off offset:-1536
	v_mul_f32_e32 v16, v32, v16
	v_mul_f32_e32 v17, v32, v17
	v_mul_f32_e32 v18, v32, v18
	v_mul_f32_e32 v19, v32, v19
	v_mul_f32_e32 v12, v60, v16
	v_mul_f32_e32 v13, v61, v17
	v_mul_f32_e32 v14, v62, v18
	v_mul_f32_e32 v15, v63, v19
	v_cvt_pk_bf16_f32 v12, v12, v13
	v_cvt_pk_bf16_f32 v13, v14, v15
	global_store_dwordx2 v[0:1], v[12:13], off offset:-1024
	v_mul_f32_e32 v16, v32, v20
	v_mul_f32_e32 v17, v32, v21
	v_mul_f32_e32 v18, v32, v22
	v_mul_f32_e32 v19, v32, v23
	v_mul_f32_e32 v12, v64, v16
	v_mul_f32_e32 v13, v65, v17
	v_mul_f32_e32 v14, v66, v18
	v_mul_f32_e32 v15, v67, v19
	v_cvt_pk_bf16_f32 v12, v12, v13
	v_cvt_pk_bf16_f32 v13, v14, v15
	global_store_dwordx2 v[0:1], v[12:13], off offset:-512
	v_mul_f32_e32 v16, v32, v24
	v_mul_f32_e32 v17, v32, v25
	v_mul_f32_e32 v18, v32, v26
	v_mul_f32_e32 v19, v32, v27
	v_mul_f32_e32 v12, v68, v16
	v_mul_f32_e32 v13, v69, v17
	v_mul_f32_e32 v14, v70, v18
	v_mul_f32_e32 v15, v71, v19
	v_cvt_pk_bf16_f32 v12, v12, v13
	v_cvt_pk_bf16_f32 v13, v14, v15
	global_store_dwordx2 v[0:1], v[12:13], off
	v_lshl_add_u64 v[0:1], v[0:1], 0, s[12:13]
	s_cmpk_lt_i32 s6, 0x4000
	s_cbranch_scc0 .LBB0_36
	s_add_i32 s6, s6, s8
	s_cmpk_lt_i32 s6, 0x4000
	s_cbranch_scc0 .Lp1_np_b
	global_load_dwordx4 v[12:15], v[4:5], off offset:-2048
	global_load_dwordx4 v[16:19], v[4:5], off offset:-1024
	global_load_dwordx4 v[20:23], v[4:5], off
	global_load_dwordx4 v[24:27], v[4:5], off offset:1024
	v_lshl_add_u64 v[4:5], v[4:5], 0, s[14:15]
	s_waitcnt vmcnt(4)
	s_branch .Lp1_go_b

.Lp1_go_b:
	v_pk_mul_f32 v[32:33], v[74:75], v[74:75]
	v_pk_mul_f32 v[34:35], v[72:73], v[72:73]
	v_pk_mul_f32 v[36:37], v[78:79], v[78:79]
	v_pk_mul_f32 v[38:39], v[76:77], v[76:77]
	v_pk_mov_b32 v[44:45], v[34:35], v[32:33] op_sel:[1,0]
	v_mov_b32_e32 v35, v33
	v_pk_mov_b32 v[32:33], v[38:39], v[36:37] op_sel:[1,0]
	v_mov_b32_e32 v39, v37
	v_mul_f32_e32 v43, v84, v84
	v_mul_f32_e32 v40, v81, v81
	v_mul_f32_e32 v42, v83, v83
	v_pk_add_f32 v[34:35], v[44:45], v[34:35]
	v_pk_add_f32 v[32:33], v[32:33], v[38:39]
	v_mul_f32_e32 v46, v85, v85
	v_mul_f32_e32 v47, v86, v86
	v_mul_f32_e32 v48, v87, v87
	v_pk_fma_f32 v[36:37], v[80:81], v[80:81], v[40:41] op_sel_hi:[1,1,0]
	v_pk_fma_f32 v[40:41], v[82:83], v[82:83], v[42:43] op_sel_hi:[1,1,0]
	v_pk_add_f32 v[34:35], v[34:35], v[34:35] op_sel:[0,1] op_sel_hi:[1,0]
	v_pk_add_f32 v[32:33], v[32:33], v[32:33] op_sel:[0,1] op_sel_hi:[1,0]
	v_mov_b32_e32 v37, v47
	v_mov_b32_e32 v41, v48
	v_mov_b32_e32 v35, v43
	v_mov_b32_e32 v33, v46
	v_pk_add_f32 v[36:37], v[36:37], v[40:41]
	v_pk_add_f32 v[32:33], v[34:35], v[32:33]
	s_nop 0
	v_pk_add_f32 v[32:33], v[32:33], v[36:37]
	s_nop 0
	v_add_f32_e32 v32, v32, v33
	ds_bpermute_b32 v33, v6, v32
	s_waitcnt lgkmcnt(0)
	v_add_f32_e32 v32, v32, v33
	ds_bpermute_b32 v33, v7, v32
	s_waitcnt lgkmcnt(0)
	v_add_f32_e32 v32, v32, v33
	ds_bpermute_b32 v33, v8, v32
	s_waitcnt lgkmcnt(0)
	v_add_f32_e32 v32, v32, v33
	ds_bpermute_b32 v33, v9, v32
	s_waitcnt lgkmcnt(0)
	v_add_f32_e32 v32, v32, v33
	ds_bpermute_b32 v33, v10, v32
	s_waitcnt lgkmcnt(0)
	v_add_f32_e32 v32, v32, v33
	ds_bpermute_b32 v33, v11, v32
	s_waitcnt lgkmcnt(0)
	v_add_f32_e32 v32, v32, v33
	v_fmamk_f32 v32, v32, 0x3a800000, v224
	v_mul_f32_e32 v33, 0x4b800000, v32
	v_cmp_gt_f32_e32 vcc, s85, v32
	s_nop 1
	v_cndmask_b32_e32 v32, v32, v33, vcc
	v_rsq_f32_e32 v32, v32
	s_nop 0
	v_mul_f32_e32 v33, 0x45800000, v32
	v_cndmask_b32_e32 v32, v32, v33, vcc
	v_mul_f32_e32 v72, v32, v72
	v_mul_f32_e32 v73, v32, v73
	v_mul_f32_e32 v74, v32, v74
	v_mul_f32_e32 v75, v32, v75
	v_mul_f32_e32 v72, v56, v72
	v_mul_f32_e32 v73, v57, v73
	v_mul_f32_e32 v74, v58, v74
	v_mul_f32_e32 v75, v59, v75
	v_cvt_pk_bf16_f32 v72, v72, v73
	v_cvt_pk_bf16_f32 v73, v74, v75
	global_store_dwordx2 v[0:1], v[72:73], off offset:-1536
	v_mul_f32_e32 v76, v32, v76
	v_mul_f32_e32 v77, v32, v77
	v_mul_f32_e32 v78, v32, v78
	v_mul_f32_e32 v79, v32, v79
	v_mul_f32_e32 v72, v60, v76
	v_mul_f32_e32 v73, v61, v77
	v_mul_f32_e32 v74, v62, v78
	v_mul_f32_e32 v75, v63, v79
	v_cvt_pk_bf16_f32 v72, v72, v73
	v_cvt_pk_bf16_f32 v73, v74, v75
	global_store_dwordx2 v[0:1], v[72:73], off offset:-1024
	v_mul_f32_e32 v76, v32, v80
	v_mul_f32_e32 v77, v32, v81
	v_mul_f32_e32 v78, v32, v82
	v_mul_f32_e32 v79, v32, v83
	v_mul_f32_e32 v72, v64, v76
	v_mul_f32_e32 v73, v65, v77
	v_mul_f32_e32 v74, v66, v78
	v_mul_f32_e32 v75, v67, v79
	v_cvt_pk_bf16_f32 v72, v72, v73
	v_cvt_pk_bf16_f32 v73, v74, v75
	global_store_dwordx2 v[0:1], v[72:73], off offset:-512
	v_mul_f32_e32 v76, v32, v84
	v_mul_f32_e32 v77, v32, v85
	v_mul_f32_e32 v78, v32, v86
	v_mul_f32_e32 v79, v32, v87
	v_mul_f32_e32 v72, v68, v76
	v_mul_f32_e32 v73, v69, v77
	v_mul_f32_e32 v74, v70, v78
	v_mul_f32_e32 v75, v71, v79
	v_cvt_pk_bf16_f32 v72, v72, v73
	v_cvt_pk_bf16_f32 v73, v74, v75
	global_store_dwordx2 v[0:1], v[72:73], off
	v_lshl_add_u64 v[0:1], v[0:1], 0, s[12:13]
	s_cmpk_lt_i32 s6, 0x4000
	s_cbranch_scc1 .LBB0_35
